# code placement: the six GEMM inner loops aligned to 64 bytes (.p2align 6 before each loop label)
# speedup vs baseline: 1.0009x; 1.0006x over previous
.LBB0_351:
	s_ashr_i32 s17, s16, 31
	s_lshl_b64 s[24:25], s[16:17], 20
	s_add_u32 s24, s10, s24
	s_addc_u32 s25, s34, s25
	s_and_b64 s[30:31], s[40:41], exec
	s_cselect_b32 s17, s25, s43
	s_cselect_b32 s18, s24, s42
	s_ashr_i32 s5, s4, 31
	s_lshl_b64 s[30:31], s[4:5], 20
	s_add_u32 s30, s26, s30
	s_addc_u32 s31, s27, s31
	s_and_b64 s[52:53], s[40:41], exec
	s_cselect_b32 s5, s31, s45
	s_cselect_b32 s20, s30, s44
	s_add_u32 s42, s42, 0x80080
	s_addc_u32 s43, s43, 0
	s_add_u32 s28, s44, 0x100
	v_mov_b32_e32 v0, 0
	s_addc_u32 s33, s45, 0
	s_mov_b32 s54, -2
	v_mov_b32_e32 v1, v0
	v_mov_b32_e32 v2, v0
	v_mov_b32_e32 v3, v0
	v_mov_b32_e32 v4, v0
	v_mov_b32_e32 v5, v0
	v_mov_b32_e32 v6, v0
	v_mov_b32_e32 v7, v0
	v_mov_b32_e32 v16, v0
	v_mov_b32_e32 v17, v0
	v_mov_b32_e32 v18, v0
	v_mov_b32_e32 v19, v0
	v_mov_b32_e32 v20, v0
	v_mov_b32_e32 v21, v0
	v_mov_b32_e32 v22, v0
	v_mov_b32_e32 v23, v0
	v_mov_b32_e32 v32, v0
	v_mov_b32_e32 v33, v0
	v_mov_b32_e32 v34, v0
	v_mov_b32_e32 v35, v0
	v_mov_b32_e32 v36, v0
	v_mov_b32_e32 v37, v0
	v_mov_b32_e32 v38, v0
	v_mov_b32_e32 v39, v0
	v_mov_b32_e32 v48, v0
	v_mov_b32_e32 v49, v0
	v_mov_b32_e32 v50, v0
	v_mov_b32_e32 v51, v0
	v_mov_b32_e32 v52, v0
	v_mov_b32_e32 v53, v0
	v_mov_b32_e32 v54, v0
	v_mov_b32_e32 v55, v0
	v_mov_b32_e32 v8, v0
	v_mov_b32_e32 v9, v0
	v_mov_b32_e32 v10, v0
	v_mov_b32_e32 v11, v0
	v_mov_b32_e32 v12, v0
	v_mov_b32_e32 v13, v0
	v_mov_b32_e32 v14, v0
	v_mov_b32_e32 v15, v0
	v_mov_b32_e32 v24, v0
	v_mov_b32_e32 v25, v0
	v_mov_b32_e32 v26, v0
	v_mov_b32_e32 v27, v0
	v_mov_b32_e32 v28, v0
	v_mov_b32_e32 v29, v0
	v_mov_b32_e32 v30, v0
	v_mov_b32_e32 v31, v0
	v_mov_b32_e32 v40, v0
	v_mov_b32_e32 v41, v0
	v_mov_b32_e32 v42, v0
	v_mov_b32_e32 v43, v0
	v_mov_b32_e32 v44, v0
	v_mov_b32_e32 v45, v0
	v_mov_b32_e32 v46, v0
	v_mov_b32_e32 v47, v0
	v_mov_b32_e32 v56, v0
	v_mov_b32_e32 v57, v0
	v_mov_b32_e32 v58, v0
	v_mov_b32_e32 v59, v0
	v_mov_b32_e32 v60, v0
	v_mov_b32_e32 v61, v0
	v_mov_b32_e32 v62, v0
	v_mov_b32_e32 v63, v0
	v_mov_b32_e32 v64, v0
	v_mov_b32_e32 v65, v0
	v_mov_b32_e32 v66, v0
	v_mov_b32_e32 v67, v0
	v_mov_b32_e32 v68, v0
	v_mov_b32_e32 v69, v0
	v_mov_b32_e32 v70, v0
	v_mov_b32_e32 v71, v0
	v_mov_b32_e32 v80, v0
	v_mov_b32_e32 v81, v0
	v_mov_b32_e32 v82, v0
	v_mov_b32_e32 v83, v0
	v_mov_b32_e32 v84, v0
	v_mov_b32_e32 v85, v0
	v_mov_b32_e32 v86, v0
	v_mov_b32_e32 v87, v0
	v_mov_b32_e32 v98, v0
	v_mov_b32_e32 v99, v0
	v_mov_b32_e32 v100, v0
	v_mov_b32_e32 v101, v0
	v_mov_b32_e32 v102, v0
	v_mov_b32_e32 v103, v0
	v_mov_b32_e32 v104, v0
	v_mov_b32_e32 v105, v0
	v_mov_b32_e32 v114, v0
	v_mov_b32_e32 v115, v0
	v_mov_b32_e32 v116, v0
	v_mov_b32_e32 v117, v0
	v_mov_b32_e32 v118, v0
	v_mov_b32_e32 v119, v0
	v_mov_b32_e32 v120, v0
	v_mov_b32_e32 v121, v0
	v_mov_b32_e32 v72, v0
	v_mov_b32_e32 v73, v0
	v_mov_b32_e32 v74, v0
	v_mov_b32_e32 v75, v0
	v_mov_b32_e32 v76, v0
	v_mov_b32_e32 v77, v0
	v_mov_b32_e32 v78, v0
	v_mov_b32_e32 v79, v0
	v_mov_b32_e32 v88, v0
	v_mov_b32_e32 v89, v0
	v_mov_b32_e32 v90, v0
	v_mov_b32_e32 v91, v0
	v_mov_b32_e32 v92, v0
	v_mov_b32_e32 v93, v0
	v_mov_b32_e32 v94, v0
	v_mov_b32_e32 v95, v0
	v_mov_b32_e32 v106, v0
	v_mov_b32_e32 v107, v0
	v_mov_b32_e32 v108, v0
	v_mov_b32_e32 v109, v0
	v_mov_b32_e32 v110, v0
	v_mov_b32_e32 v111, v0
	v_mov_b32_e32 v112, v0
	v_mov_b32_e32 v113, v0
	v_mov_b32_e32 v122, v0
	v_mov_b32_e32 v123, v0
	v_mov_b32_e32 v124, v0
	v_mov_b32_e32 v125, v0
	v_mov_b32_e32 v126, v0
	v_mov_b32_e32 v127, v0
	v_mov_b32_e32 v128, v0
	v_mov_b32_e32 v129, v0
	.p2align	6

.LBB0_635:
	s_ashr_i32 s43, s42, 31
	s_lshl_b64 s[44:45], s[42:43], 18
	s_add_u32 s44, s2, s44
	s_addc_u32 s45, s3, s45
	s_and_b64 s[50:51], s[40:41], exec
	s_cselect_b32 s35, s45, s69
	s_cselect_b32 s43, s44, s68
	s_ashr_i32 s31, s30, 31
	s_lshl_b64 s[50:51], s[30:31], 18
	s_add_u32 s52, s16, s50
	s_addc_u32 s53, s17, s51
	s_and_b64 s[50:51], s[40:41], exec
	s_cselect_b32 s31, s53, s83
	s_cselect_b32 s50, s52, s82
	s_add_u32 s68, s68, 0x20080
	s_addc_u32 s69, s69, 0
	s_add_u32 s51, s82, 0x100
	v_mov_b32_e32 v0, 0
	s_addc_u32 s54, s83, 0
	s_mov_b32 s55, -2
	v_mov_b32_e32 v1, v0
	v_mov_b32_e32 v2, v0
	v_mov_b32_e32 v3, v0
	v_mov_b32_e32 v4, v0
	v_mov_b32_e32 v5, v0
	v_mov_b32_e32 v6, v0
	v_mov_b32_e32 v7, v0
	v_mov_b32_e32 v8, v0
	v_mov_b32_e32 v9, v0
	v_mov_b32_e32 v10, v0
	v_mov_b32_e32 v11, v0
	v_mov_b32_e32 v12, v0
	v_mov_b32_e32 v13, v0
	v_mov_b32_e32 v14, v0
	v_mov_b32_e32 v15, v0
	v_mov_b32_e32 v24, v0
	v_mov_b32_e32 v25, v0
	v_mov_b32_e32 v26, v0
	v_mov_b32_e32 v27, v0
	v_mov_b32_e32 v28, v0
	v_mov_b32_e32 v29, v0
	v_mov_b32_e32 v30, v0
	v_mov_b32_e32 v31, v0
	v_mov_b32_e32 v40, v0
	v_mov_b32_e32 v41, v0
	v_mov_b32_e32 v42, v0
	v_mov_b32_e32 v43, v0
	v_mov_b32_e32 v44, v0
	v_mov_b32_e32 v45, v0
	v_mov_b32_e32 v46, v0
	v_mov_b32_e32 v47, v0
	v_mov_b32_e32 v16, v0
	v_mov_b32_e32 v17, v0
	v_mov_b32_e32 v18, v0
	v_mov_b32_e32 v19, v0
	v_mov_b32_e32 v20, v0
	v_mov_b32_e32 v21, v0
	v_mov_b32_e32 v22, v0
	v_mov_b32_e32 v23, v0
	v_mov_b32_e32 v32, v0
	v_mov_b32_e32 v33, v0
	v_mov_b32_e32 v34, v0
	v_mov_b32_e32 v35, v0
	v_mov_b32_e32 v36, v0
	v_mov_b32_e32 v37, v0
	v_mov_b32_e32 v38, v0
	v_mov_b32_e32 v39, v0
	v_mov_b32_e32 v48, v0
	v_mov_b32_e32 v49, v0
	v_mov_b32_e32 v50, v0
	v_mov_b32_e32 v51, v0
	v_mov_b32_e32 v52, v0
	v_mov_b32_e32 v53, v0
	v_mov_b32_e32 v54, v0
	v_mov_b32_e32 v55, v0
	v_mov_b32_e32 v56, v0
	v_mov_b32_e32 v57, v0
	v_mov_b32_e32 v58, v0
	v_mov_b32_e32 v59, v0
	v_mov_b32_e32 v60, v0
	v_mov_b32_e32 v61, v0
	v_mov_b32_e32 v62, v0
	v_mov_b32_e32 v63, v0
	v_mov_b32_e32 v64, v0
	v_mov_b32_e32 v65, v0
	v_mov_b32_e32 v66, v0
	v_mov_b32_e32 v67, v0
	v_mov_b32_e32 v68, v0
	v_mov_b32_e32 v69, v0
	v_mov_b32_e32 v70, v0
	v_mov_b32_e32 v71, v0
	v_mov_b32_e32 v72, v0
	v_mov_b32_e32 v73, v0
	v_mov_b32_e32 v74, v0
	v_mov_b32_e32 v75, v0
	v_mov_b32_e32 v76, v0
	v_mov_b32_e32 v77, v0
	v_mov_b32_e32 v78, v0
	v_mov_b32_e32 v79, v0
	v_mov_b32_e32 v88, v0
	v_mov_b32_e32 v89, v0
	v_mov_b32_e32 v90, v0
	v_mov_b32_e32 v91, v0
	v_mov_b32_e32 v92, v0
	v_mov_b32_e32 v93, v0
	v_mov_b32_e32 v94, v0
	v_mov_b32_e32 v95, v0
	v_mov_b32_e32 v106, v0
	v_mov_b32_e32 v107, v0
	v_mov_b32_e32 v108, v0
	v_mov_b32_e32 v109, v0
	v_mov_b32_e32 v110, v0
	v_mov_b32_e32 v111, v0
	v_mov_b32_e32 v112, v0
	v_mov_b32_e32 v113, v0
	v_mov_b32_e32 v80, v0
	v_mov_b32_e32 v81, v0
	v_mov_b32_e32 v82, v0
	v_mov_b32_e32 v83, v0
	v_mov_b32_e32 v84, v0
	v_mov_b32_e32 v85, v0
	v_mov_b32_e32 v86, v0
	v_mov_b32_e32 v87, v0
	v_mov_b32_e32 v98, v0
	v_mov_b32_e32 v99, v0
	v_mov_b32_e32 v100, v0
	v_mov_b32_e32 v101, v0
	v_mov_b32_e32 v102, v0
	v_mov_b32_e32 v103, v0
	v_mov_b32_e32 v104, v0
	v_mov_b32_e32 v105, v0
	v_mov_b32_e32 v114, v0
	v_mov_b32_e32 v115, v0
	v_mov_b32_e32 v116, v0
	v_mov_b32_e32 v117, v0
	v_mov_b32_e32 v118, v0
	v_mov_b32_e32 v119, v0
	v_mov_b32_e32 v120, v0
	v_mov_b32_e32 v121, v0
	v_mov_b32_e32 v122, v0
	v_mov_b32_e32 v123, v0
	v_mov_b32_e32 v124, v0
	v_mov_b32_e32 v125, v0
	v_mov_b32_e32 v126, v0
	v_mov_b32_e32 v127, v0
	v_mov_b32_e32 v128, v0
	v_mov_b32_e32 v129, v0
	.p2align	6

.LBB0_655:
	s_ashr_i32 s43, s42, 31
	s_lshl_b64 s[44:45], s[42:43], 18
	s_add_u32 s44, s10, s44
	s_addc_u32 s45, s12, s45
	s_and_b64 s[52:53], s[40:41], exec
	s_cselect_b32 s43, s45, s69
	s_cselect_b32 s51, s44, s68
	s_ashr_i32 s31, s30, 31
	s_lshl_b64 s[52:53], s[30:31], 18
	s_add_u32 s52, s2, s52
	s_addc_u32 s53, s3, s53
	s_and_b64 s[54:55], s[40:41], exec
	s_cselect_b32 s31, s53, s83
	s_cselect_b32 s54, s52, s82
	s_add_u32 s68, s68, 0x20080
	s_addc_u32 s69, s69, 0
	s_add_u32 s55, s82, 0x100
	v_mov_b32_e32 v0, 0
	s_addc_u32 s56, s83, 0
	s_mov_b32 s57, -2
	v_mov_b32_e32 v1, v0
	v_mov_b32_e32 v2, v0
	v_mov_b32_e32 v3, v0
	v_mov_b32_e32 v4, v0
	v_mov_b32_e32 v5, v0
	v_mov_b32_e32 v6, v0
	v_mov_b32_e32 v7, v0
	v_mov_b32_e32 v8, v0
	v_mov_b32_e32 v9, v0
	v_mov_b32_e32 v10, v0
	v_mov_b32_e32 v11, v0
	v_mov_b32_e32 v12, v0
	v_mov_b32_e32 v13, v0
	v_mov_b32_e32 v14, v0
	v_mov_b32_e32 v15, v0
	v_mov_b32_e32 v24, v0
	v_mov_b32_e32 v25, v0
	v_mov_b32_e32 v26, v0
	v_mov_b32_e32 v27, v0
	v_mov_b32_e32 v28, v0
	v_mov_b32_e32 v29, v0
	v_mov_b32_e32 v30, v0
	v_mov_b32_e32 v31, v0
	v_mov_b32_e32 v40, v0
	v_mov_b32_e32 v41, v0
	v_mov_b32_e32 v42, v0
	v_mov_b32_e32 v43, v0
	v_mov_b32_e32 v44, v0
	v_mov_b32_e32 v45, v0
	v_mov_b32_e32 v46, v0
	v_mov_b32_e32 v47, v0
	v_mov_b32_e32 v16, v0
	v_mov_b32_e32 v17, v0
	v_mov_b32_e32 v18, v0
	v_mov_b32_e32 v19, v0
	v_mov_b32_e32 v20, v0
	v_mov_b32_e32 v21, v0
	v_mov_b32_e32 v22, v0
	v_mov_b32_e32 v23, v0
	v_mov_b32_e32 v32, v0
	v_mov_b32_e32 v33, v0
	v_mov_b32_e32 v34, v0
	v_mov_b32_e32 v35, v0
	v_mov_b32_e32 v36, v0
	v_mov_b32_e32 v37, v0
	v_mov_b32_e32 v38, v0
	v_mov_b32_e32 v39, v0
	v_mov_b32_e32 v48, v0
	v_mov_b32_e32 v49, v0
	v_mov_b32_e32 v50, v0
	v_mov_b32_e32 v51, v0
	v_mov_b32_e32 v52, v0
	v_mov_b32_e32 v53, v0
	v_mov_b32_e32 v54, v0
	v_mov_b32_e32 v55, v0
	v_mov_b32_e32 v56, v0
	v_mov_b32_e32 v57, v0
	v_mov_b32_e32 v58, v0
	v_mov_b32_e32 v59, v0
	v_mov_b32_e32 v60, v0
	v_mov_b32_e32 v61, v0
	v_mov_b32_e32 v62, v0
	v_mov_b32_e32 v63, v0
	v_mov_b32_e32 v64, v0
	v_mov_b32_e32 v65, v0
	v_mov_b32_e32 v66, v0
	v_mov_b32_e32 v67, v0
	v_mov_b32_e32 v68, v0
	v_mov_b32_e32 v69, v0
	v_mov_b32_e32 v70, v0
	v_mov_b32_e32 v71, v0
	v_mov_b32_e32 v72, v0
	v_mov_b32_e32 v73, v0
	v_mov_b32_e32 v74, v0
	v_mov_b32_e32 v75, v0
	v_mov_b32_e32 v76, v0
	v_mov_b32_e32 v77, v0
	v_mov_b32_e32 v78, v0
	v_mov_b32_e32 v79, v0
	v_mov_b32_e32 v88, v0
	v_mov_b32_e32 v89, v0
	v_mov_b32_e32 v90, v0
	v_mov_b32_e32 v91, v0
	v_mov_b32_e32 v92, v0
	v_mov_b32_e32 v93, v0
	v_mov_b32_e32 v94, v0
	v_mov_b32_e32 v95, v0
	v_mov_b32_e32 v106, v0
	v_mov_b32_e32 v107, v0
	v_mov_b32_e32 v108, v0
	v_mov_b32_e32 v109, v0
	v_mov_b32_e32 v110, v0
	v_mov_b32_e32 v111, v0
	v_mov_b32_e32 v112, v0
	v_mov_b32_e32 v113, v0
	v_mov_b32_e32 v80, v0
	v_mov_b32_e32 v81, v0
	v_mov_b32_e32 v82, v0
	v_mov_b32_e32 v83, v0
	v_mov_b32_e32 v84, v0
	v_mov_b32_e32 v85, v0
	v_mov_b32_e32 v86, v0
	v_mov_b32_e32 v87, v0
	v_mov_b32_e32 v98, v0
	v_mov_b32_e32 v99, v0
	v_mov_b32_e32 v100, v0
	v_mov_b32_e32 v101, v0
	v_mov_b32_e32 v102, v0
	v_mov_b32_e32 v103, v0
	v_mov_b32_e32 v104, v0
	v_mov_b32_e32 v105, v0
	v_mov_b32_e32 v114, v0
	v_mov_b32_e32 v115, v0
	v_mov_b32_e32 v116, v0
	v_mov_b32_e32 v117, v0
	v_mov_b32_e32 v118, v0
	v_mov_b32_e32 v119, v0
	v_mov_b32_e32 v120, v0
	v_mov_b32_e32 v121, v0
	v_mov_b32_e32 v122, v0
	v_mov_b32_e32 v123, v0
	v_mov_b32_e32 v124, v0
	v_mov_b32_e32 v125, v0
	v_mov_b32_e32 v126, v0
	v_mov_b32_e32 v127, v0
	v_mov_b32_e32 v128, v0
	v_mov_b32_e32 v129, v0
	.p2align	6

.LBB0_1037:
	s_ashr_i32 s53, s52, 31
	s_lshl_b64 s[34:35], s[52:53], 20
	s_add_u32 s68, s50, s34
	s_addc_u32 s69, s51, s35
	s_and_b64 s[34:35], s[42:43], exec
	s_cselect_b32 s10, s69, s45
	s_cselect_b32 s12, s68, s44
	s_ashr_i32 s31, s30, 31
	s_lshl_b64 s[34:35], s[30:31], 20
	s_add_u32 s82, s46, s34
	s_addc_u32 s83, s47, s35
	s_and_b64 s[34:35], s[42:43], exec
	s_cselect_b32 s18, s83, s85
	s_cselect_b32 s20, s82, s84
	s_add_u32 s44, s44, 0x80080
	s_addc_u32 s45, s45, 0
	s_add_u32 s28, s84, 0x100
	v_mov_b32_e32 v0, 0
	s_addc_u32 s31, s85, 0
	s_mov_b32 s33, -2
	v_mov_b32_e32 v1, v0
	v_mov_b32_e32 v2, v0
	v_mov_b32_e32 v3, v0
	v_mov_b32_e32 v4, v0
	v_mov_b32_e32 v5, v0
	v_mov_b32_e32 v6, v0
	v_mov_b32_e32 v7, v0
	v_mov_b32_e32 v16, v0
	v_mov_b32_e32 v17, v0
	v_mov_b32_e32 v18, v0
	v_mov_b32_e32 v19, v0
	v_mov_b32_e32 v20, v0
	v_mov_b32_e32 v21, v0
	v_mov_b32_e32 v22, v0
	v_mov_b32_e32 v23, v0
	v_mov_b32_e32 v32, v0
	v_mov_b32_e32 v33, v0
	v_mov_b32_e32 v34, v0
	v_mov_b32_e32 v35, v0
	v_mov_b32_e32 v36, v0
	v_mov_b32_e32 v37, v0
	v_mov_b32_e32 v38, v0
	v_mov_b32_e32 v39, v0
	v_mov_b32_e32 v48, v0
	v_mov_b32_e32 v49, v0
	v_mov_b32_e32 v50, v0
	v_mov_b32_e32 v51, v0
	v_mov_b32_e32 v52, v0
	v_mov_b32_e32 v53, v0
	v_mov_b32_e32 v54, v0
	v_mov_b32_e32 v55, v0
	v_mov_b32_e32 v8, v0
	v_mov_b32_e32 v9, v0
	v_mov_b32_e32 v10, v0
	v_mov_b32_e32 v11, v0
	v_mov_b32_e32 v12, v0
	v_mov_b32_e32 v13, v0
	v_mov_b32_e32 v14, v0
	v_mov_b32_e32 v15, v0
	v_mov_b32_e32 v24, v0
	v_mov_b32_e32 v25, v0
	v_mov_b32_e32 v26, v0
	v_mov_b32_e32 v27, v0
	v_mov_b32_e32 v28, v0
	v_mov_b32_e32 v29, v0
	v_mov_b32_e32 v30, v0
	v_mov_b32_e32 v31, v0
	v_mov_b32_e32 v40, v0
	v_mov_b32_e32 v41, v0
	v_mov_b32_e32 v42, v0
	v_mov_b32_e32 v43, v0
	v_mov_b32_e32 v44, v0
	v_mov_b32_e32 v45, v0
	v_mov_b32_e32 v46, v0
	v_mov_b32_e32 v47, v0
	v_mov_b32_e32 v56, v0
	v_mov_b32_e32 v57, v0
	v_mov_b32_e32 v58, v0
	v_mov_b32_e32 v59, v0
	v_mov_b32_e32 v60, v0
	v_mov_b32_e32 v61, v0
	v_mov_b32_e32 v62, v0
	v_mov_b32_e32 v63, v0
	v_mov_b32_e32 v64, v0
	v_mov_b32_e32 v65, v0
	v_mov_b32_e32 v66, v0
	v_mov_b32_e32 v67, v0
	v_mov_b32_e32 v68, v0
	v_mov_b32_e32 v69, v0
	v_mov_b32_e32 v70, v0
	v_mov_b32_e32 v71, v0
	v_mov_b32_e32 v80, v0
	v_mov_b32_e32 v81, v0
	v_mov_b32_e32 v82, v0
	v_mov_b32_e32 v83, v0
	v_mov_b32_e32 v84, v0
	v_mov_b32_e32 v85, v0
	v_mov_b32_e32 v86, v0
	v_mov_b32_e32 v87, v0
	v_mov_b32_e32 v98, v0
	v_mov_b32_e32 v99, v0
	v_mov_b32_e32 v100, v0
	v_mov_b32_e32 v101, v0
	v_mov_b32_e32 v102, v0
	v_mov_b32_e32 v103, v0
	v_mov_b32_e32 v104, v0
	v_mov_b32_e32 v105, v0
	v_mov_b32_e32 v114, v0
	v_mov_b32_e32 v115, v0
	v_mov_b32_e32 v116, v0
	v_mov_b32_e32 v117, v0
	v_mov_b32_e32 v118, v0
	v_mov_b32_e32 v119, v0
	v_mov_b32_e32 v120, v0
	v_mov_b32_e32 v121, v0
	v_mov_b32_e32 v72, v0
	v_mov_b32_e32 v73, v0
	v_mov_b32_e32 v74, v0
	v_mov_b32_e32 v75, v0
	v_mov_b32_e32 v76, v0
	v_mov_b32_e32 v77, v0
	v_mov_b32_e32 v78, v0
	v_mov_b32_e32 v79, v0
	v_mov_b32_e32 v88, v0
	v_mov_b32_e32 v89, v0
	v_mov_b32_e32 v90, v0
	v_mov_b32_e32 v91, v0
	v_mov_b32_e32 v92, v0
	v_mov_b32_e32 v93, v0
	v_mov_b32_e32 v94, v0
	v_mov_b32_e32 v95, v0
	v_mov_b32_e32 v106, v0
	v_mov_b32_e32 v107, v0
	v_mov_b32_e32 v108, v0
	v_mov_b32_e32 v109, v0
	v_mov_b32_e32 v110, v0
	v_mov_b32_e32 v111, v0
	v_mov_b32_e32 v112, v0
	v_mov_b32_e32 v113, v0
	v_mov_b32_e32 v122, v0
	v_mov_b32_e32 v123, v0
	v_mov_b32_e32 v124, v0
	v_mov_b32_e32 v125, v0
	v_mov_b32_e32 v126, v0
	v_mov_b32_e32 v127, v0
	v_mov_b32_e32 v128, v0
	v_mov_b32_e32 v129, v0
	.p2align	6

.LBB0_1264:
	s_ashr_i32 s17, s16, 31
	s_lshl_b64 s[24:25], s[16:17], 22
	s_add_u32 s24, s51, s24
	s_addc_u32 s25, s58, s25
	s_and_b64 s[30:31], s[40:41], exec
	s_cselect_b32 s12, s25, s43
	s_cselect_b32 s17, s24, s42
	s_ashr_i32 s5, s4, 31
	s_lshl_b64 s[30:31], s[4:5], 22
	s_add_u32 s30, s27, s30
	s_addc_u32 s31, s50, s31
	s_and_b64 s[52:53], s[40:41], exec
	s_cselect_b32 s5, s31, s45
	s_cselect_b32 s18, s30, s44
	s_add_u32 s42, s42, 0x200080
	s_addc_u32 s43, s43, 0
	s_add_u32 s20, s44, 0x100
	v_mov_b32_e32 v0, 0
	s_addc_u32 s28, s45, 0
	s_mov_b32 s33, -2
	v_mov_b32_e32 v1, v0
	v_mov_b32_e32 v2, v0
	v_mov_b32_e32 v3, v0
	v_mov_b32_e32 v4, v0
	v_mov_b32_e32 v5, v0
	v_mov_b32_e32 v6, v0
	v_mov_b32_e32 v7, v0
	v_mov_b32_e32 v16, v0
	v_mov_b32_e32 v17, v0
	v_mov_b32_e32 v18, v0
	v_mov_b32_e32 v19, v0
	v_mov_b32_e32 v20, v0
	v_mov_b32_e32 v21, v0
	v_mov_b32_e32 v22, v0
	v_mov_b32_e32 v23, v0
	v_mov_b32_e32 v32, v0
	v_mov_b32_e32 v33, v0
	v_mov_b32_e32 v34, v0
	v_mov_b32_e32 v35, v0
	v_mov_b32_e32 v36, v0
	v_mov_b32_e32 v37, v0
	v_mov_b32_e32 v38, v0
	v_mov_b32_e32 v39, v0
	v_mov_b32_e32 v48, v0
	v_mov_b32_e32 v49, v0
	v_mov_b32_e32 v50, v0
	v_mov_b32_e32 v51, v0
	v_mov_b32_e32 v52, v0
	v_mov_b32_e32 v53, v0
	v_mov_b32_e32 v54, v0
	v_mov_b32_e32 v55, v0
	v_mov_b32_e32 v8, v0
	v_mov_b32_e32 v9, v0
	v_mov_b32_e32 v10, v0
	v_mov_b32_e32 v11, v0
	v_mov_b32_e32 v12, v0
	v_mov_b32_e32 v13, v0
	v_mov_b32_e32 v14, v0
	v_mov_b32_e32 v15, v0
	v_mov_b32_e32 v24, v0
	v_mov_b32_e32 v25, v0
	v_mov_b32_e32 v26, v0
	v_mov_b32_e32 v27, v0
	v_mov_b32_e32 v28, v0
	v_mov_b32_e32 v29, v0
	v_mov_b32_e32 v30, v0
	v_mov_b32_e32 v31, v0
	v_mov_b32_e32 v40, v0
	v_mov_b32_e32 v41, v0
	v_mov_b32_e32 v42, v0
	v_mov_b32_e32 v43, v0
	v_mov_b32_e32 v44, v0
	v_mov_b32_e32 v45, v0
	v_mov_b32_e32 v46, v0
	v_mov_b32_e32 v47, v0
	v_mov_b32_e32 v56, v0
	v_mov_b32_e32 v57, v0
	v_mov_b32_e32 v58, v0
	v_mov_b32_e32 v59, v0
	v_mov_b32_e32 v60, v0
	v_mov_b32_e32 v61, v0
	v_mov_b32_e32 v62, v0
	v_mov_b32_e32 v63, v0
	v_mov_b32_e32 v64, v0
	v_mov_b32_e32 v65, v0
	v_mov_b32_e32 v66, v0
	v_mov_b32_e32 v67, v0
	v_mov_b32_e32 v68, v0
	v_mov_b32_e32 v69, v0
	v_mov_b32_e32 v70, v0
	v_mov_b32_e32 v71, v0
	v_mov_b32_e32 v80, v0
	v_mov_b32_e32 v81, v0
	v_mov_b32_e32 v82, v0
	v_mov_b32_e32 v83, v0
	v_mov_b32_e32 v84, v0
	v_mov_b32_e32 v85, v0
	v_mov_b32_e32 v86, v0
	v_mov_b32_e32 v87, v0
	v_mov_b32_e32 v98, v0
	v_mov_b32_e32 v99, v0
	v_mov_b32_e32 v100, v0
	v_mov_b32_e32 v101, v0
	v_mov_b32_e32 v102, v0
	v_mov_b32_e32 v103, v0
	v_mov_b32_e32 v104, v0
	v_mov_b32_e32 v105, v0
	v_mov_b32_e32 v114, v0
	v_mov_b32_e32 v115, v0
	v_mov_b32_e32 v116, v0
	v_mov_b32_e32 v117, v0
	v_mov_b32_e32 v118, v0
	v_mov_b32_e32 v119, v0
	v_mov_b32_e32 v120, v0
	v_mov_b32_e32 v121, v0
	v_mov_b32_e32 v72, v0
	v_mov_b32_e32 v73, v0
	v_mov_b32_e32 v74, v0
	v_mov_b32_e32 v75, v0
	v_mov_b32_e32 v76, v0
	v_mov_b32_e32 v77, v0
	v_mov_b32_e32 v78, v0
	v_mov_b32_e32 v79, v0
	v_mov_b32_e32 v88, v0
	v_mov_b32_e32 v89, v0
	v_mov_b32_e32 v90, v0
	v_mov_b32_e32 v91, v0
	v_mov_b32_e32 v92, v0
	v_mov_b32_e32 v93, v0
	v_mov_b32_e32 v94, v0
	v_mov_b32_e32 v95, v0
	v_mov_b32_e32 v106, v0
	v_mov_b32_e32 v107, v0
	v_mov_b32_e32 v108, v0
	v_mov_b32_e32 v109, v0
	v_mov_b32_e32 v110, v0
	v_mov_b32_e32 v111, v0
	v_mov_b32_e32 v112, v0
	v_mov_b32_e32 v113, v0
	v_mov_b32_e32 v122, v0
	v_mov_b32_e32 v123, v0
	v_mov_b32_e32 v124, v0
	v_mov_b32_e32 v125, v0
	v_mov_b32_e32 v126, v0
	v_mov_b32_e32 v127, v0
	v_mov_b32_e32 v128, v0
	v_mov_b32_e32 v129, v0
	.p2align	6

.LBB0_1283:
	s_ashr_i32 s25, s24, 31
	s_lshl_b64 s[30:31], s[24:25], 20
	s_add_u32 s30, s10, s30
	s_addc_u32 s31, s27, s31
	s_and_b64 s[38:39], s[42:43], exec
	s_cselect_b32 s3, s31, s53
	s_cselect_b32 s12, s30, s52
	s_ashr_i32 s17, s16, 31
	s_lshl_b64 s[38:39], s[16:17], 20
	s_add_u32 s44, s14, s38
	s_addc_u32 s45, s26, s39
	s_and_b64 s[38:39], s[42:43], exec
	s_cselect_b32 s17, s45, s69
	s_cselect_b32 s18, s44, s68
	s_add_u32 s52, s52, 0x80080
	s_addc_u32 s53, s53, 0
	s_add_u32 s20, s68, 0x100
	v_mov_b32_e32 v0, 0
	s_addc_u32 s25, s69, 0
	s_mov_b32 s28, -2
	v_mov_b32_e32 v1, v0
	v_mov_b32_e32 v2, v0
	v_mov_b32_e32 v3, v0
	v_mov_b32_e32 v4, v0
	v_mov_b32_e32 v5, v0
	v_mov_b32_e32 v6, v0
	v_mov_b32_e32 v7, v0
	v_mov_b32_e32 v16, v0
	v_mov_b32_e32 v17, v0
	v_mov_b32_e32 v18, v0
	v_mov_b32_e32 v19, v0
	v_mov_b32_e32 v20, v0
	v_mov_b32_e32 v21, v0
	v_mov_b32_e32 v22, v0
	v_mov_b32_e32 v23, v0
	v_mov_b32_e32 v32, v0
	v_mov_b32_e32 v33, v0
	v_mov_b32_e32 v34, v0
	v_mov_b32_e32 v35, v0
	v_mov_b32_e32 v36, v0
	v_mov_b32_e32 v37, v0
	v_mov_b32_e32 v38, v0
	v_mov_b32_e32 v39, v0
	v_mov_b32_e32 v48, v0
	v_mov_b32_e32 v49, v0
	v_mov_b32_e32 v50, v0
	v_mov_b32_e32 v51, v0
	v_mov_b32_e32 v52, v0
	v_mov_b32_e32 v53, v0
	v_mov_b32_e32 v54, v0
	v_mov_b32_e32 v55, v0
	v_mov_b32_e32 v8, v0
	v_mov_b32_e32 v9, v0
	v_mov_b32_e32 v10, v0
	v_mov_b32_e32 v11, v0
	v_mov_b32_e32 v12, v0
	v_mov_b32_e32 v13, v0
	v_mov_b32_e32 v14, v0
	v_mov_b32_e32 v15, v0
	v_mov_b32_e32 v24, v0
	v_mov_b32_e32 v25, v0
	v_mov_b32_e32 v26, v0
	v_mov_b32_e32 v27, v0
	v_mov_b32_e32 v28, v0
	v_mov_b32_e32 v29, v0
	v_mov_b32_e32 v30, v0
	v_mov_b32_e32 v31, v0
	v_mov_b32_e32 v40, v0
	v_mov_b32_e32 v41, v0
	v_mov_b32_e32 v42, v0
	v_mov_b32_e32 v43, v0
	v_mov_b32_e32 v44, v0
	v_mov_b32_e32 v45, v0
	v_mov_b32_e32 v46, v0
	v_mov_b32_e32 v47, v0
	v_mov_b32_e32 v56, v0
	v_mov_b32_e32 v57, v0
	v_mov_b32_e32 v58, v0
	v_mov_b32_e32 v59, v0
	v_mov_b32_e32 v60, v0
	v_mov_b32_e32 v61, v0
	v_mov_b32_e32 v62, v0
	v_mov_b32_e32 v63, v0
	v_mov_b32_e32 v64, v0
	v_mov_b32_e32 v65, v0
	v_mov_b32_e32 v66, v0
	v_mov_b32_e32 v67, v0
	v_mov_b32_e32 v68, v0
	v_mov_b32_e32 v69, v0
	v_mov_b32_e32 v70, v0
	v_mov_b32_e32 v71, v0
	v_mov_b32_e32 v80, v0
	v_mov_b32_e32 v81, v0
	v_mov_b32_e32 v82, v0
	v_mov_b32_e32 v83, v0
	v_mov_b32_e32 v84, v0
	v_mov_b32_e32 v85, v0
	v_mov_b32_e32 v86, v0
	v_mov_b32_e32 v87, v0
	v_mov_b32_e32 v98, v0
	v_mov_b32_e32 v99, v0
	v_mov_b32_e32 v100, v0
	v_mov_b32_e32 v101, v0
	v_mov_b32_e32 v102, v0
	v_mov_b32_e32 v103, v0
	v_mov_b32_e32 v104, v0
	v_mov_b32_e32 v105, v0
	v_mov_b32_e32 v114, v0
	v_mov_b32_e32 v115, v0
	v_mov_b32_e32 v116, v0
	v_mov_b32_e32 v117, v0
	v_mov_b32_e32 v118, v0
	v_mov_b32_e32 v119, v0
	v_mov_b32_e32 v120, v0
	v_mov_b32_e32 v121, v0
	v_mov_b32_e32 v72, v0
	v_mov_b32_e32 v73, v0
	v_mov_b32_e32 v74, v0
	v_mov_b32_e32 v75, v0
	v_mov_b32_e32 v76, v0
	v_mov_b32_e32 v77, v0
	v_mov_b32_e32 v78, v0
	v_mov_b32_e32 v79, v0
	v_mov_b32_e32 v88, v0
	v_mov_b32_e32 v89, v0
	v_mov_b32_e32 v90, v0
	v_mov_b32_e32 v91, v0
	v_mov_b32_e32 v92, v0
	v_mov_b32_e32 v93, v0
	v_mov_b32_e32 v94, v0
	v_mov_b32_e32 v95, v0
	v_mov_b32_e32 v106, v0
	v_mov_b32_e32 v107, v0
	v_mov_b32_e32 v108, v0
	v_mov_b32_e32 v109, v0
	v_mov_b32_e32 v110, v0
	v_mov_b32_e32 v111, v0
	v_mov_b32_e32 v112, v0
	v_mov_b32_e32 v113, v0
	v_mov_b32_e32 v122, v0
	v_mov_b32_e32 v123, v0
	v_mov_b32_e32 v124, v0
	v_mov_b32_e32 v125, v0
	v_mov_b32_e32 v126, v0
	v_mov_b32_e32 v127, v0
	v_mov_b32_e32 v128, v0
	v_mov_b32_e32 v129, v0
	.p2align	6
